# fox attention loop restructured like diff: waves 0-3 MFMA-then-softmax, waves 4-7 softmax-then-MFMA, K one tile ahead of V, decay-bias k-step last
# baseline (speedup 1.0000x reference)
; template <bool DIFF>
; __device__ __forceinline__ void attn_unit(const AttnP& A, int b, int h, int qi, ldsp lds) {
;     ...
;     LOAD_TILE(kt0);
;     STORE_TILE(kt0 & 1);
;     __syncthreads();
;     float cq = 0.f;
;     if (!DIFF) cq = pref[q_pp >> 6] + A.cumloc[(Rb + q_pp) * 8 + h];
;     float mhat = 0.f, l_run = 0.f;
;     f32x16 negm;
; #pragma unroll
;     for (int r = 0; r < 16; ++r) negm[r] = 0.f;
;     f32x16 o[NTD];
; #pragma unroll
;     for (int t = 0; t < NTD; ++t)
; #pragma unroll
;         for (int r = 0; r < 16; ++r) o[t][r] = 0.f;
;     const int trb = (4 * hi + ((lane & 15) >> 2)) * VP + ((lane >> 4) & 1) * 32 + (lane & 3) * 8;
;     for (int kt = kt0; kt < nt; ++kt) {
;         if (kt + 1 < nt) LOAD_TILE(kt + 1);
;         if (64 * kt <= qmax_w) {
;             ldsp Kb = lds + (kt & 1) * STAGE; ldsp Vb = Kb + 64 * KP;
;             bf16x8 kf[8]; bf16x8 ka0, ka1, qa; f32x16 s0, s1;
.LBB0_463:
	s_or_b64 exec, exec, s[0:1]
	s_cmp_gt_i32 s93, s91
	v_lshlrev_b32_e32 v151, 2, v12
	s_waitcnt lgkmcnt(0)
	s_barrier
	s_cbranch_scc1 .LBB0_486
	s_ashr_i32 s0, s40, 6
	s_lshl_b32 s0, s0, 2
	s_add_i32 s0, s82, s0
	v_lshlrev_b64 v[2:3], 5, v[2:3]
	v_mov_b32_e32 v6, s0
	v_lshl_add_u64 v[2:3], s[54:55], 0, v[2:3]
	s_lshl_b32 s0, s41, 2
	s_mov_b32 s1, s35
	v_lshl_add_u64 v[2:3], v[2:3], 0, s[0:1]
	global_load_dword v2, v[2:3], off
	ds_read_b32 v6, v6
	s_add_i32 s1, s91, -3
	s_and_b64 s[46:47], s[16:17], exec
	s_cselect_b32 s95, s1, 0
	s_or_b32 s96, s40, 31
	s_add_u32 s72, s54, s0
	s_addc_u32 s73, s55, 0
	s_lshl_b32 s0, s93, 2
	v_mov_b32_e32 v165, 0
	v_and_b32_e32 v163, 24, v7
	s_mov_b32 s94, 0
	v_mul_u32_u24_e32 v164, 0x90, v10
	v_cmp_gt_u32_e64 s[46:47], 32, v11
	v_lshl_add_u64 v[152:153], s[58:59], 0, v[4:5]
	s_add_i32 s97, s82, s0
	s_lshl_b32 s98, s93, 6
	v_mov_b32_e32 v154, 0
	v_mov_b32_e32 v34, 0
	v_mov_b32_e32 v35, v165
	v_mov_b32_e32 v36, v165
	v_mov_b32_e32 v37, v165
	v_mov_b32_e32 v38, v165
	v_mov_b32_e32 v39, v165
	v_mov_b32_e32 v40, v165
	v_mov_b32_e32 v41, v165
	v_mov_b32_e32 v42, v165
	v_mov_b32_e32 v43, v165
	v_mov_b32_e32 v44, v165
	v_mov_b32_e32 v45, v165
	v_mov_b32_e32 v46, v165
	v_mov_b32_e32 v47, v165
	v_mov_b32_e32 v48, v165
	v_mov_b32_e32 v49, v165
	v_mov_b32_e32 v18, 0
	v_mov_b32_e32 v19, v165
	v_mov_b32_e32 v20, v165
	v_mov_b32_e32 v21, v165
	v_mov_b32_e32 v22, v165
	v_mov_b32_e32 v23, v165
	v_mov_b32_e32 v24, v165
	v_mov_b32_e32 v25, v165
	v_mov_b32_e32 v26, v165
	v_mov_b32_e32 v27, v165
	v_mov_b32_e32 v28, v165
	v_mov_b32_e32 v29, v165
	v_mov_b32_e32 v30, v165
	v_mov_b32_e32 v31, v165
	v_mov_b32_e32 v32, v165
	v_mov_b32_e32 v33, v165
	v_mov_b32_e32 v3, v165
	v_mov_b32_e32 v4, v165
	v_mov_b32_e32 v5, v165
	v_mov_b32_e32 v7, v165
	v_mov_b32_e32 v8, v165
	v_mov_b32_e32 v9, v165
	v_mov_b32_e32 v10, v165
	v_mov_b32_e32 v11, v165
	v_mov_b32_e32 v12, v165
	v_mov_b32_e32 v13, v165
	v_mov_b32_e32 v14, v165
	v_mov_b32_e32 v15, v165
	v_mov_b32_e32 v16, v165
	v_mov_b32_e32 v17, v165
	s_waitcnt vmcnt(0) lgkmcnt(0)
	v_add_f32_e32 v160, v6, v2
	v_lshrrev_b32_e32 v2, 2, v148
	v_and_or_b32 v2, v2, 3, v151
	v_mul_u32_u24_e32 v161, 0xc0, v2
	v_lshlrev_b32_e32 v2, 1, v148
	v_and_b32_e32 v162, 32, v2
	v_mov_b32_e32 v2, v165
	v_mov_b32_e32 v6, v165
	s_lshr_b32 s64, s96, 6
	s_add_i32 s64, s64, 1
	s_add_i32 s0, s91, 1
	s_min_i32 s64, s64, s0
	v_add_u32_e32 v156, v156, v157
	v_add_u32_e32 v158, v158, v157
	v_add3_u32 v161, v161, v162, v163
	v_add_u32_e32 v150, v164, v150
	s_lshl_b64 s[40:41], s[22:23], 13
	v_lshl_add_u64 v[152:153], v[152:153], 0, s[40:41]
	v_lshl_add_u64 v[152:153], v[152:153], 0, v[0:1]
	s_mov_b32 s65, s35
	s_lshl_b32 s0, s93, 19
	s_mov_b32 s1, s35
	s_lshr_b32 s1, s93, 13
	v_lshl_add_u64 v[152:153], v[152:153], 0, s[0:1]
	s_or_b32 s0, s92, 0xc00
	s_lshl_b32 s0, s0, 1
	s_mov_b32 s1, s35
	v_lshl_add_u64 v[250:251], v[152:153], 0, s[0:1]
	v_lshl_add_u64 v[250:251], v[250:251], 0, s[26:27]
	v_lshl_add_u64 v[152:153], v[152:153], 0, s[34:35]
	v_lshl_add_u64 v[152:153], v[152:153], 0, s[26:27]
	s_add_i32 s0, s93, 1
	s_lshl_b32 s0, s0, 6
	s_mov_b32 s1, s35
	s_add_u32 s0, s0, s22
	s_addc_u32 s1, s1, s23
	v_lshl_add_u64 v[252:253], s[0:1], 0, v[148:149]
	v_lshlrev_b64 v[252:253], 5, v[252:253]
	v_lshl_add_u64 v[252:253], s[72:73], 0, v[252:253]
	s_cmp_ge_i32 s93, s91
	s_cbranch_scc1 .Lfx_noinit
	global_load_dwordx4 v[98:101], v[152:153], off
	v_lshl_add_u64 v[152:153], v[152:153], 0, s[26:27]
	s_and_saveexec_b64 s[0:1], s[44:45]
	global_load_dword v155, v[252:253], off
	s_mov_b64 exec, s[0:1]
	s_mov_b64 s[0:1], 0x800
	v_lshl_add_u64 v[252:253], v[252:253], 0, s[0:1]
.Lfx_noinit:
	s_mov_b32 s99, s93
	v_readfirstlane_b32 s0, v148
	s_cmp_gt_u32 s0, 255
	s_cbranch_scc1 .Lfb_top
.Lfa_top:
	s_bitcmp1_b32 s99, 0
	s_cselect_b32 s74, 0x5500, 0
	s_sub_i32 s75, 0x5500, s74
	s_cmp_eq_u32 s99, s93
	s_cbranch_scc1 .Lfa_first
	s_cmp_gt_i32 s99, s64
	s_cbranch_scc1 .Lfa_idle
	s_cmp_eq_u32 s99, s64
	s_cbranch_scc1 .Lfa_last
	v_add_u32_e32 v169, s74, v150
	v_add_u32_e32 v0, s74, v164
	v_add_u32_e32 v168, s75, v161
	ds_read_b64_tr_b16 v[106:107], v168 offset:9216
	ds_read_b64_tr_b16 v[108:109], v168 offset:10752
	ds_read_b64_tr_b16 v[110:111], v168 offset:9280
	ds_read_b64_tr_b16 v[112:113], v168 offset:10816
	ds_read_b64_tr_b16 v[116:117], v168 offset:12288
	ds_read_b64_tr_b16 v[118:119], v168 offset:13824
	ds_read_b64_tr_b16 v[120:121], v168 offset:12352
	ds_read_b64_tr_b16 v[122:123], v168 offset:13888
	ds_read_b64_tr_b16 v[124:125], v168 offset:15360
	ds_read_b64_tr_b16 v[126:127], v168 offset:16896
	ds_read_b64_tr_b16 v[128:129], v168 offset:15424
	ds_read_b64_tr_b16 v[130:131], v168 offset:16960
	ds_read_b64_tr_b16 v[132:133], v168 offset:18432
	ds_read_b64_tr_b16 v[134:135], v168 offset:19968
	ds_read_b64_tr_b16 v[136:137], v168 offset:18496
	ds_read_b64_tr_b16 v[138:139], v168 offset:20032
	v_mov_b32_e32 v248, s97
	ds_read_b32 v248, v248
	ds_read_b128 v[170:173], v169
	ds_read_b128 v[244:247], v169 offset:4608
	s_waitcnt lgkmcnt(15)
	v_mfma_f32_32x32x16_bf16 v[18:33], v[106:109], v[66:69], v[18:33]
	ds_read_b128 v[106:109], v169 offset:32
	s_waitcnt lgkmcnt(15)
	v_mfma_f32_32x32x16_bf16 v[2:17], v[110:113], v[66:69], v[2:17]
	ds_read_b128 v[110:113], v169 offset:4640
	s_waitcnt lgkmcnt(15)
	v_mfma_f32_32x32x16_bf16 v[18:33], v[116:119], v[70:73], v[18:33]
	ds_read_b128 v[116:119], v169 offset:64
	s_waitcnt lgkmcnt(14)
	v_mfma_f32_32x32x16_bf16 v[2:17], v[120:123], v[70:73], v[2:17]
	ds_read_b128 v[120:123], v169 offset:4672
	s_waitcnt lgkmcnt(13)
	v_mfma_f32_32x32x16_bf16 v[18:33], v[124:127], v[50:53], v[18:33]
	ds_read_b128 v[124:127], v169 offset:96
	s_waitcnt lgkmcnt(12)
	v_mfma_f32_32x32x16_bf16 v[2:17], v[128:131], v[50:53], v[2:17]
	ds_read_b128 v[128:131], v169 offset:4704
	s_waitcnt lgkmcnt(11)
	v_mfma_f32_32x32x16_bf16 v[18:33], v[132:135], v[54:57], v[18:33]
	ds_read_b128 v[132:135], v0 offset:128
	s_waitcnt lgkmcnt(10)
	v_mfma_f32_32x32x16_bf16 v[2:17], v[136:139], v[54:57], v[2:17]
	ds_read_b128 v[136:139], v0 offset:4736
	s_waitcnt lgkmcnt(9)
	v_mfma_f32_32x32x16_bf16 v[66:81], v[170:173], v[90:93], v[34:49]
	s_waitcnt lgkmcnt(8)
	v_mfma_f32_32x32x16_bf16 v[50:65], v[244:247], v[90:93], v[34:49]
	v_sub_f32_e32 v249, v160, v248
	v_cvt_pk_bf16_f32 v162, v249, 0
	v_lshlrev_b32_e32 v162, 16, v162
	s_waitcnt lgkmcnt(7)
	v_mfma_f32_32x32x16_bf16 v[66:81], v[106:109], v[82:85], v[66:81]
	s_waitcnt lgkmcnt(6)
	v_mfma_f32_32x32x16_bf16 v[50:65], v[110:113], v[82:85], v[50:65]
	v_sub_f32_e32 v249, v249, v162
	v_cvt_pk_bf16_f32 v163, v249, 0
	v_and_b32_e32 v157, 0xffff, v163
	v_lshlrev_b32_e32 v163, 16, v163
	s_waitcnt lgkmcnt(5)
	v_mfma_f32_32x32x16_bf16 v[66:81], v[116:119], v[86:89], v[66:81]
	s_waitcnt lgkmcnt(4)
	v_mfma_f32_32x32x16_bf16 v[50:65], v[120:123], v[86:89], v[50:65]
	v_sub_f32_e32 v249, v249, v163
	v_cvt_pk_bf16_f32 v249, v249, 0
	v_or_b32_e32 v162, 0x3f80, v162
	v_lshl_or_b32 v249, v249, 16, v157
	v_cndmask_b32_e64 v140, 0, v114, s[46:47]
	v_cndmask_b32_e64 v142, 0, v249, s[46:47]
	v_cndmask_b32_e64 v141, 0, v162, s[46:47]
	v_mov_b32_e32 v143, v1
	s_waitcnt lgkmcnt(3)
	v_mfma_f32_32x32x16_bf16 v[66:81], v[124:127], v[94:97], v[66:81]
	s_waitcnt lgkmcnt(2)
	v_mfma_f32_32x32x16_bf16 v[50:65], v[128:131], v[94:97], v[50:65]
	s_waitcnt lgkmcnt(1)
	v_mfma_f32_32x32x16_bf16 v[66:81], v[132:135], v[140:143], v[66:81]
	s_waitcnt lgkmcnt(0)
	v_mfma_f32_32x32x16_bf16 v[50:65], v[136:139], v[140:143], v[50:65]
.Lfa_postqk:
	s_waitcnt vmcnt(0)
	s_cmp_ge_i32 s99, s91
	s_cbranch_scc1 .Lfx2_snok
	v_add_u32_e32 v115, s75, v156
	ds_write_b128 v115, v[98:101]
	s_and_saveexec_b64 s[0:1], s[44:45]
	v_xor_b32_e32 v248, 0x80000000, v155
	v_cvt_pk_bf16_f32 v248, v248, 0
	v_lshlrev_b32_e32 v249, 16, v248
	v_sub_f32_e64 v249, -v155, v249
	v_cvt_pk_bf16_f32 v162, v249, 0
	v_lshlrev_b32_e32 v162, 16, v162
	v_sub_f32_e32 v249, v249, v162
	v_cvt_pk_bf16_f32 v249, v249, 0
	v_and_or_b32 v112, v248, s83, v162
	v_and_or_b32 v113, v249, s83, 1.0
	v_mov_b32_e32 v115, v1
	v_add_u32_e32 v248, s75, v159
	ds_write_b128 v248, v[112:115] offset:128
	s_mov_b64 exec, s[0:1]
.Lfx2_snok:
	s_cmp_gt_i32 s99, s91
	s_cbranch_scc1 .Lfx1_snov
	s_cmp_eq_u32 s99, s93
	s_cbranch_scc1 .Lfx1_snov
	v_add_u32_e32 v115, s74, v158
	ds_write_b128 v115, v[102:105] offset:9216
.Lfx1_snov:
	s_cmp_ge_i32 s99, s91
	s_cbranch_scc1 .Lfx3_nold
	global_load_dwordx4 v[102:105], v[250:251], off
	v_lshl_add_u64 v[250:251], v[250:251], 0, s[26:27]
	s_add_i32 s0, s99, 1
	s_cmp_ge_i32 s0, s91
	s_cbranch_scc1 .Lfx3_nold
	global_load_dwordx4 v[98:101], v[152:153], off
	v_lshl_add_u64 v[152:153], v[152:153], 0, s[26:27]
	s_and_saveexec_b64 s[0:1], s[44:45]
	global_load_dword v155, v[252:253], off
	s_mov_b64 exec, s[0:1]
	s_mov_b64 s[0:1], 0x800
	v_lshl_add_u64 v[252:253], v[252:253], 0, s[0:1]
.Lfx3_nold:
	s_nop 7
	s_nop 3
	s_cmp_lg_u32 s99, 0
	s_cselect_b64 s[40:41], -1, 0
	s_cmp_lt_i32 s99, s95
	s_cselect_b64 s[48:49], -1, 0
	s_and_b64 s[50:51], s[40:41], s[48:49]
	s_and_b64 vcc, exec, s[50:51]
	s_cbranch_vccnz .Lfx5_nomask
	v_add_u32_e32 v141, s98, v151
	v_cmp_gt_i32_e32 vcc, 48, v141
	v_cmp_gt_i32_e64 s[48:49], v141, v146
	s_or_b64 vcc, vcc, s[48:49]
	v_add_u32_e32 v142, 32, v141
	v_cndmask_b32_e32 v66, v66, v223, vcc
	v_cmp_gt_i32_e32 vcc, 16, v141
	v_cmp_gt_i32_e64 s[48:49], v142, v146
	s_or_b64 vcc, vcc, s[48:49]
	v_add_u32_e32 v142, 1, v141
	v_cndmask_b32_e32 v50, v50, v223, vcc
	v_cmp_gt_i32_e32 vcc, 48, v142
	v_cmp_ge_i32_e64 s[48:49], v141, v146
	s_or_b64 vcc, s[48:49], vcc
	v_cndmask_b32_e32 v67, v67, v223, vcc
	v_cmp_gt_i32_e32 vcc, 16, v142
	v_add_u32_e32 v142, 33, v141
	v_cmp_gt_i32_e64 s[48:49], v142, v146
	s_or_b64 vcc, vcc, s[48:49]
	v_add_u32_e32 v142, 2, v141
	v_cndmask_b32_e32 v51, v51, v223, vcc
	v_cmp_gt_i32_e32 vcc, 48, v142
	v_cmp_gt_i32_e64 s[48:49], v142, v146
	s_or_b64 vcc, vcc, s[48:49]
	v_cndmask_b32_e32 v68, v68, v223, vcc
	v_cmp_gt_i32_e32 vcc, 16, v142
	v_add_u32_e32 v142, 34, v141
	v_cmp_gt_i32_e64 s[48:49], v142, v146
	s_or_b64 vcc, vcc, s[48:49]
	v_add_u32_e32 v142, 3, v141
	v_cndmask_b32_e32 v52, v52, v223, vcc
	v_cmp_gt_i32_e32 vcc, 48, v142
	v_cmp_gt_i32_e64 s[48:49], v142, v146
	s_or_b64 vcc, vcc, s[48:49]
	v_cndmask_b32_e32 v69, v69, v223, vcc
	v_cmp_gt_i32_e32 vcc, 16, v142
	v_add_u32_e32 v142, 35, v141
	v_cmp_gt_i32_e64 s[48:49], v142, v146
	s_or_b64 vcc, vcc, s[48:49]
	v_add_u32_e32 v142, 8, v141
	v_cndmask_b32_e32 v53, v53, v223, vcc
	v_cmp_gt_i32_e32 vcc, 48, v142
	v_cmp_gt_i32_e64 s[48:49], v142, v146
	s_or_b64 vcc, vcc, s[48:49]
	v_cndmask_b32_e32 v70, v70, v223, vcc
	v_cmp_gt_i32_e32 vcc, 16, v142
	v_add_u32_e32 v142, 40, v141
	v_cmp_gt_i32_e64 s[48:49], v142, v146
	s_or_b64 vcc, vcc, s[48:49]
	v_add_u32_e32 v142, 9, v141
	v_cndmask_b32_e32 v54, v54, v223, vcc
	v_cmp_gt_i32_e32 vcc, 48, v142
	v_cmp_gt_i32_e64 s[48:49], v142, v146
	s_or_b64 vcc, vcc, s[48:49]
	v_cndmask_b32_e32 v71, v71, v223, vcc
	v_cmp_gt_i32_e32 vcc, 16, v142
	v_add_u32_e32 v142, 41, v141
	v_cmp_gt_i32_e64 s[48:49], v142, v146
	s_or_b64 vcc, vcc, s[48:49]
	v_add_u32_e32 v142, 10, v141
	v_cndmask_b32_e32 v55, v55, v223, vcc
	v_cmp_gt_i32_e32 vcc, 48, v142
	v_cmp_gt_i32_e64 s[48:49], v142, v146
	s_or_b64 vcc, vcc, s[48:49]
	v_cndmask_b32_e32 v72, v72, v223, vcc
	v_cmp_gt_i32_e32 vcc, 16, v142
	v_add_u32_e32 v142, 42, v141
	v_cmp_gt_i32_e64 s[48:49], v142, v146
; #define EXPSUM_BLOCK() do { psa = 0.f; psb = 0.f; \
;             _Pragma("unroll") for (int r = 0; r < 16; ++r) { s0[r] = __builtin_amdgcn_exp2f(s0[r]); s1[r] = __builtin_amdgcn_exp2f(s1[r]); psa += s0[r]; asm("" : "+v"(psa)); psb += s1[r]; asm("" : "+v"(psb)); } } while (0)
; template <bool DIFF>
; __device__ __forceinline__ void attn_unit(const AttnP& A, int b, int h, int qi, ldsp lds) {
;     ...
;             bool full = (kt == kt0);
;             float psa, psb;
;             if (!full) {
;                 EXPSUM_BLOCK();
;                 if (__any(psa + psb > 1.0e18f)) { full = true; QK_BLOCK();
	s_or_b64 vcc, vcc, s[48:49]
	v_add_u32_e32 v142, 11, v141
	v_cndmask_b32_e32 v56, v56, v223, vcc
	v_cmp_gt_i32_e32 vcc, 48, v142
	v_cmp_gt_i32_e64 s[48:49], v142, v146
	s_or_b64 vcc, vcc, s[48:49]
	v_cndmask_b32_e32 v73, v73, v223, vcc
	v_cmp_gt_i32_e32 vcc, 16, v142
	v_add_u32_e32 v142, 43, v141
	v_cmp_gt_i32_e64 s[48:49], v142, v146
	s_or_b64 vcc, vcc, s[48:49]
	v_add_u32_e32 v142, 16, v141
	v_cndmask_b32_e32 v57, v57, v223, vcc
	v_cmp_gt_i32_e32 vcc, 48, v142
	v_cmp_gt_i32_e64 s[48:49], v142, v146
	s_or_b64 vcc, vcc, s[48:49]
	s_cmp_lt_i32 s99, 0
	v_add_u32_e32 v142, 48, v141
	v_cndmask_b32_e32 v74, v74, v223, vcc
	s_cselect_b64 s[40:41], -1, 0
	v_cmp_gt_i32_e32 vcc, v142, v146
	s_or_b64 vcc, s[40:41], vcc
	v_add_u32_e32 v142, 17, v141
	v_cndmask_b32_e32 v58, v58, v223, vcc
	v_cmp_gt_i32_e32 vcc, 48, v142
	v_cmp_gt_i32_e64 s[48:49], v142, v146
	s_or_b64 vcc, vcc, s[48:49]
	v_add_u32_e32 v142, 49, v141
	v_cndmask_b32_e32 v75, v75, v223, vcc
	v_cmp_gt_i32_e32 vcc, v142, v146
	s_or_b64 vcc, s[40:41], vcc
	v_add_u32_e32 v142, 18, v141
	v_cndmask_b32_e32 v59, v59, v223, vcc
	v_cmp_gt_i32_e32 vcc, 48, v142
	v_cmp_gt_i32_e64 s[48:49], v142, v146
	s_or_b64 vcc, vcc, s[48:49]
	v_add_u32_e32 v142, 50, v141
	v_cndmask_b32_e32 v76, v76, v223, vcc
	v_cmp_gt_i32_e32 vcc, v142, v146
	s_or_b64 vcc, s[40:41], vcc
	v_add_u32_e32 v142, 19, v141
	v_cndmask_b32_e32 v60, v60, v223, vcc
	v_cmp_gt_i32_e32 vcc, 48, v142
	v_cmp_gt_i32_e64 s[48:49], v142, v146
	s_or_b64 vcc, vcc, s[48:49]
	v_add_u32_e32 v142, 51, v141
	v_cndmask_b32_e32 v77, v77, v223, vcc
	v_cmp_gt_i32_e32 vcc, v142, v146
	s_or_b64 vcc, s[40:41], vcc
	v_add_u32_e32 v142, 24, v141
	v_cndmask_b32_e32 v61, v61, v223, vcc
	v_cmp_gt_i32_e32 vcc, 48, v142
	v_cmp_gt_i32_e64 s[48:49], v142, v146
	s_or_b64 vcc, vcc, s[48:49]
	v_add_u32_e32 v142, 56, v141
	v_cndmask_b32_e32 v78, v78, v223, vcc
	v_cmp_gt_i32_e32 vcc, v142, v146
	s_or_b64 vcc, s[40:41], vcc
	v_add_u32_e32 v142, 25, v141
	v_cndmask_b32_e32 v62, v62, v223, vcc
	v_cmp_gt_i32_e32 vcc, 48, v142
	v_cmp_gt_i32_e64 s[48:49], v142, v146
	s_or_b64 vcc, vcc, s[48:49]
	v_add_u32_e32 v142, 57, v141
	v_cndmask_b32_e32 v79, v79, v223, vcc
	v_cmp_gt_i32_e32 vcc, v142, v146
	s_or_b64 vcc, s[40:41], vcc
	v_add_u32_e32 v142, 26, v141
	v_cndmask_b32_e32 v63, v63, v223, vcc
	v_cmp_gt_i32_e32 vcc, 48, v142
	v_cmp_gt_i32_e64 s[48:49], v142, v146
	s_or_b64 vcc, vcc, s[48:49]
	v_add_u32_e32 v142, 58, v141
	v_cndmask_b32_e32 v80, v80, v223, vcc
	v_cmp_gt_i32_e32 vcc, v142, v146
	s_or_b64 vcc, s[40:41], vcc
	v_add_u32_e32 v142, 27, v141
	v_cndmask_b32_e32 v64, v64, v223, vcc
	v_cmp_gt_i32_e32 vcc, 48, v142
	v_cmp_gt_i32_e64 s[48:49], v142, v146
	s_or_b64 vcc, vcc, s[48:49]
	v_add_u32_e32 v141, 59, v141
	v_cndmask_b32_e32 v81, v81, v223, vcc
	v_cmp_gt_i32_e32 vcc, v141, v146
	s_or_b64 vcc, s[40:41], vcc
	s_nop 0
	v_cndmask_b32_e32 v65, v65, v223, vcc
.Lfx5_nomask:
	s_cmp_eq_u32 s99, s93
	s_cselect_b64 s[48:49], -1, 0
	s_and_b64 vcc, exec, s[48:49]
	s_cbranch_vccnz .Lfx6_full
	v_exp_f32_e32 v106, v66
	v_exp_f32_e32 v124, v50
	v_exp_f32_e32 v107, v67
	v_exp_f32_e32 v125, v51
	v_add_f32_e32 v166, 0, v106
	v_add_f32_e32 v167, 0, v124
	v_exp_f32_e32 v108, v68
	v_exp_f32_e32 v126, v52
	v_add_f32_e32 v166, v107, v166
	v_add_f32_e32 v167, v125, v167
	v_exp_f32_e32 v109, v69
	v_exp_f32_e32 v127, v53
	v_add_f32_e32 v166, v108, v166
	v_add_f32_e32 v167, v126, v167
	v_exp_f32_e32 v110, v70
	v_exp_f32_e32 v128, v54
	v_add_f32_e32 v166, v109, v166
	v_add_f32_e32 v167, v127, v167
	v_exp_f32_e32 v111, v71
	v_exp_f32_e32 v129, v55
	v_add_f32_e32 v166, v110, v166
	v_add_f32_e32 v167, v128, v167
	v_exp_f32_e32 v112, v72
	v_exp_f32_e32 v130, v56
	v_add_f32_e32 v166, v111, v166
	v_add_f32_e32 v167, v129, v167
	v_exp_f32_e32 v113, v73
	v_exp_f32_e32 v131, v57
	v_add_f32_e32 v166, v112, v166
	v_add_f32_e32 v167, v130, v167
	v_exp_f32_e32 v116, v74
	v_exp_f32_e32 v132, v58
	v_add_f32_e32 v166, v113, v166
	v_add_f32_e32 v167, v131, v167
	v_exp_f32_e32 v117, v75
	v_exp_f32_e32 v133, v59
	v_add_f32_e32 v166, v116, v166
	v_add_f32_e32 v167, v132, v167
	v_exp_f32_e32 v118, v76
	v_exp_f32_e32 v134, v60
	v_add_f32_e32 v166, v117, v166
	v_add_f32_e32 v167, v133, v167
	v_exp_f32_e32 v119, v77
	v_exp_f32_e32 v135, v61
	v_add_f32_e32 v166, v118, v166
	v_add_f32_e32 v167, v134, v167
	v_exp_f32_e32 v120, v78
	v_exp_f32_e32 v136, v62
	v_add_f32_e32 v166, v119, v166
	v_add_f32_e32 v167, v135, v167
	v_exp_f32_e32 v121, v79
	v_exp_f32_e32 v137, v63
	v_add_f32_e32 v166, v120, v166
	v_add_f32_e32 v167, v136, v167
	v_exp_f32_e32 v122, v80
	v_exp_f32_e32 v138, v64
	v_add_f32_e32 v166, v121, v166
	v_add_f32_e32 v167, v137, v167
	v_exp_f32_e32 v123, v81
	v_exp_f32_e32 v139, v65
	v_add_f32_e32 v166, v122, v166
	v_add_f32_e32 v167, v138, v167
	s_nop 0
	v_add_f32_e32 v166, v123, v166
	v_add_f32_e32 v167, v139, v167
	v_add_f32_e32 v141, v166, v167
	v_cmp_lt_f32_e32 vcc, s85, v141
	s_cbranch_vccz .Lfx7_pack
; __device__ __forceinline__ float swap32_max(float m) { auto rr = __builtin_amdgcn_permlane32_swap(__float_as_uint(m), __float_as_uint(m), false, false); return fmaxf(__uint_as_float(rr[0]), __uint_as_float(rr[1])); }
; #define EXPSUM_BLOCK() do { psa = 0.f; psb = 0.f; \
;             _Pragma("unroll") for (int r = 0; r < 16; ++r) { s0[r] = __builtin_amdgcn_exp2f(s0[r]); s1[r] = __builtin_amdgcn_exp2f(s1[r]); psa += s0[r]; asm("" : "+v"(psa)); psb += s1[r]; asm("" : "+v"(psb)); } } while (0)
; template <bool DIFF>
; __device__ __forceinline__ void attn_unit(const AttnP& A, int b, int h, int qi, ldsp lds) {
;     ...
;             if (full) {
;                 float ma = fmaxf(fmaxf(s0[0], s0[1]), s1[0]), mb = fmaxf(fmaxf(s0[2], s0[3]), s1[1]);
;                 ma = fmaxf(fmaxf(ma, s1[2]), s1[3]);
; #pragma unroll
;                 for (int r = 4; r < 16; r += 4) { ma = fmaxf(fmaxf(ma, s0[r]), s0[r + 1]); mb = fmaxf(fmaxf(mb, s0[r + 2]), s0[r + 3]); ma = fmaxf(fmaxf(ma, s1[r]), s1[r + 1]); mb = fmaxf(fmaxf(mb, s1[r + 2]), s1[r + 3]); }
;                 const float rm = swap32_max(fmaxf(ma, mb));
;                 const float dl = (kt == kt0) ? ((rm == -INFINITY) ? 0.f : rm) : fmaxf(rm, 0.f);
;                 mhat += dl;
; #pragma unroll
;                 for (int r = 0; r < 16; ++r) { s0[r] -= dl; s1[r] -= dl; negm[r] = -mhat; }
;                 const float f = (kt == kt0) ? 1.0f : __builtin_amdgcn_exp2f(-dl);
;                 l_run *= f;
; #pragma unroll
;                 for (int t = 0; t < NTD; ++t)
; #pragma unroll
;                     for (int r = 0; r < 16; ++r) o[t][r] *= f;
;                 EXPSUM_BLOCK();
.Lfx6_full:
	v_max_f32_e32 v141, v66, v67
	v_max3_f32 v142, v68, v69, v51
	v_max3_f32 v141, v141, v50, v52
	v_max3_f32 v141, v141, v53, v70
	v_max3_f32 v142, v142, v72, v73
	v_max3_f32 v141, v141, v71, v54
	v_max3_f32 v142, v142, v56, v57
	v_max3_f32 v141, v141, v55, v74
	v_max3_f32 v142, v142, v76, v77
	v_max3_f32 v141, v141, v75, v58
	v_max3_f32 v142, v142, v60, v61
	v_max3_f32 v141, v141, v59, v78
	v_max3_f32 v142, v142, v80, v81
	v_max3_f32 v141, v141, v79, v62
	v_max3_f32 v142, v142, v64, v65
	v_max3_f32 v141, v141, v63, v142
	v_mov_b32_e32 v142, v141
	s_nop 1
	v_permlane32_swap_b32_e32 v141, v142
	s_nop 1
	v_max_f32_e32 v141, v141, v142
	v_cmp_neq_f32_e32 vcc, s84, v141
	s_nop 1
	v_cndmask_b32_e32 v142, 0, v141, vcc
	v_max_f32_e32 v141, 0, v141
	s_nop 0
	v_cndmask_b32_e64 v142, v141, v142, s[48:49]
	v_exp_f32_e64 v141, -v142
	v_add_f32_e32 v165, v165, v142
	s_nop 0
	v_cndmask_b32_e64 v141, v141, 1.0, s[48:49]
	v_mul_f32_e32 v154, v154, v141
	v_mul_f32_e32 v2, v2, v141
	v_mul_f32_e32 v3, v3, v141
	v_mul_f32_e32 v4, v4, v141
	v_mul_f32_e32 v5, v5, v141
	v_mul_f32_e32 v6, v6, v141
	v_mul_f32_e32 v7, v7, v141
	v_mul_f32_e32 v8, v8, v141
	v_mul_f32_e32 v9, v9, v141
	v_mul_f32_e32 v10, v10, v141
	v_mul_f32_e32 v11, v11, v141
	v_mul_f32_e32 v12, v12, v141
	v_mul_f32_e32 v13, v13, v141
	v_mul_f32_e32 v14, v14, v141
	v_mul_f32_e32 v15, v15, v141
	v_mul_f32_e32 v16, v16, v141
	v_mul_f32_e32 v17, v17, v141
	v_mul_f32_e32 v18, v18, v141
	v_mul_f32_e32 v19, v19, v141
	v_mul_f32_e32 v20, v20, v141
	v_mul_f32_e32 v21, v21, v141
	v_mul_f32_e32 v22, v22, v141
	v_mul_f32_e32 v23, v23, v141
	v_mul_f32_e32 v24, v24, v141
	v_mul_f32_e32 v25, v25, v141
	v_mul_f32_e32 v26, v26, v141
	v_mul_f32_e32 v27, v27, v141
	v_mul_f32_e32 v28, v28, v141
	v_mul_f32_e32 v29, v29, v141
	v_mul_f32_e32 v30, v30, v141
	v_mul_f32_e32 v31, v31, v141
	v_mul_f32_e32 v32, v32, v141
	v_mul_f32_e32 v33, v33, v141
	v_xor_b32_e32 v34, 0x80000000, v165
	v_mov_b32_e32 v35, v34
	v_mov_b32_e32 v36, v34
	v_mov_b32_e32 v37, v34
	v_mov_b32_e32 v38, v34
	v_mov_b32_e32 v39, v34
	v_mov_b32_e32 v40, v34
	v_mov_b32_e32 v41, v34
	v_mov_b32_e32 v42, v34
	v_mov_b32_e32 v43, v34
	v_mov_b32_e32 v44, v34
	v_mov_b32_e32 v45, v34
	v_mov_b32_e32 v46, v34
	v_mov_b32_e32 v47, v34
	v_mov_b32_e32 v48, v34
	v_mov_b32_e32 v49, v34
	v_sub_f32_e32 v106, v66, v142
	v_sub_f32_e32 v124, v50, v142
	v_sub_f32_e32 v107, v67, v142
	v_sub_f32_e32 v125, v51, v142
	v_sub_f32_e32 v108, v68, v142
	v_sub_f32_e32 v126, v52, v142
	v_sub_f32_e32 v109, v69, v142
	v_sub_f32_e32 v127, v53, v142
	v_sub_f32_e32 v110, v70, v142
	v_sub_f32_e32 v128, v54, v142
	v_sub_f32_e32 v111, v71, v142
	v_sub_f32_e32 v129, v55, v142
	v_sub_f32_e32 v112, v72, v142
	v_sub_f32_e32 v130, v56, v142
	v_sub_f32_e32 v113, v73, v142
	v_sub_f32_e32 v131, v57, v142
	v_sub_f32_e32 v116, v74, v142
	v_sub_f32_e32 v132, v58, v142
	v_sub_f32_e32 v117, v75, v142
	v_sub_f32_e32 v133, v59, v142
	v_sub_f32_e32 v118, v76, v142
	v_sub_f32_e32 v134, v60, v142
	v_sub_f32_e32 v119, v77, v142
	v_sub_f32_e32 v135, v61, v142
	v_sub_f32_e32 v120, v78, v142
	v_sub_f32_e32 v136, v62, v142
	v_sub_f32_e32 v121, v79, v142
	v_sub_f32_e32 v137, v63, v142
	v_sub_f32_e32 v122, v80, v142
	v_sub_f32_e32 v138, v64, v142
	v_sub_f32_e32 v123, v81, v142
	v_sub_f32_e32 v139, v65, v142
	v_exp_f32_e32 v106, v106
	v_exp_f32_e32 v124, v124
	v_exp_f32_e32 v107, v107
	v_exp_f32_e32 v125, v125
	v_add_f32_e32 v166, 0, v106
	v_add_f32_e32 v167, 0, v124
	v_exp_f32_e32 v108, v108
	v_exp_f32_e32 v126, v126
	v_add_f32_e32 v166, v107, v166
	v_add_f32_e32 v167, v125, v167
	v_exp_f32_e32 v109, v109
	v_exp_f32_e32 v127, v127
	v_add_f32_e32 v166, v108, v166
	v_add_f32_e32 v167, v126, v167
	v_exp_f32_e32 v110, v110
	v_exp_f32_e32 v128, v128
	v_add_f32_e32 v166, v109, v166
	v_add_f32_e32 v167, v127, v167
	v_exp_f32_e32 v111, v111
	v_exp_f32_e32 v129, v129
	v_add_f32_e32 v166, v110, v166
	v_add_f32_e32 v167, v128, v167
	v_exp_f32_e32 v112, v112
	v_exp_f32_e32 v130, v130
	v_add_f32_e32 v166, v111, v166
	v_add_f32_e32 v167, v129, v167
	v_exp_f32_e32 v113, v113
	v_exp_f32_e32 v131, v131
	v_add_f32_e32 v166, v112, v166
	v_add_f32_e32 v167, v130, v167
	v_exp_f32_e32 v116, v116
	v_exp_f32_e32 v132, v132
	v_add_f32_e32 v166, v113, v166
	v_add_f32_e32 v167, v131, v167
	v_exp_f32_e32 v117, v117
	v_exp_f32_e32 v133, v133
	v_add_f32_e32 v166, v116, v166
	v_add_f32_e32 v167, v132, v167
	v_exp_f32_e32 v118, v118
	v_exp_f32_e32 v134, v134
	v_add_f32_e32 v166, v117, v166
	v_add_f32_e32 v167, v133, v167
	v_exp_f32_e32 v119, v119
	v_exp_f32_e32 v135, v135
	v_add_f32_e32 v166, v118, v166
	v_add_f32_e32 v167, v134, v167
	v_exp_f32_e32 v120, v120
	v_exp_f32_e32 v136, v136
	v_add_f32_e32 v166, v119, v166
	v_add_f32_e32 v167, v135, v167
	v_exp_f32_e32 v121, v121
	v_exp_f32_e32 v137, v137
	v_add_f32_e32 v166, v120, v166
	v_add_f32_e32 v167, v136, v167
	v_exp_f32_e32 v122, v122
	v_exp_f32_e32 v138, v138
	v_add_f32_e32 v166, v121, v166
	v_add_f32_e32 v167, v137, v167
	v_exp_f32_e32 v123, v123
	v_exp_f32_e32 v139, v139
	v_add_f32_e32 v166, v122, v166
	v_add_f32_e32 v167, v138, v167
	s_nop 0
	v_add_f32_e32 v166, v123, v166
	v_add_f32_e32 v167, v139, v167
; __device__ __forceinline__ unsigned cvtpk(float lo, float hi) { f32x2 v = {lo, hi}; bf16x2_t b = __builtin_convertvector(v, bf16x2_t); return __builtin_bit_cast(unsigned, b); }
; template <bool DIFF>
; __device__ __forceinline__ void attn_unit(const AttnP& A, int b, int h, int qi, ldsp lds) {
;     ...
;             bf16x8 pw[4];
; #pragma unroll
;             for (int j = 0; j < 4; ++j) {
;                 u32x4 pk;
;                 if (j < 2) { const int rb = 8 * (j & 1); pk.x = cvtpk(s0[rb], s0[rb + 1]); pk.y = cvtpk(s0[rb + 2], s0[rb + 3]); pk.z = cvtpk(s0[rb + 4], s0[rb + 5]); pk.w = cvtpk(s0[rb + 6], s0[rb + 7]); }
;                 else { const int rb = 8 * (j & 1); pk.x = cvtpk(s1[rb], s1[rb + 1]); pk.y = cvtpk(s1[rb + 2], s1[rb + 3]); pk.z = cvtpk(s1[rb + 4], s1[rb + 5]); pk.w = cvtpk(s1[rb + 6], s1[rb + 7]); }
;                 pw[j] = __builtin_bit_cast(bf16x8, pk);
;             }
;             __builtin_amdgcn_sched_barrier(0);
;             __builtin_amdgcn_s_setprio(1);
; #pragma unroll
;             for (int t = 0; t < 2; ++t)
; #pragma unroll
;                 for (int j = 0; j < 4; ++j) {
;                     const bf16x8 vf = (bf16x8){vlo[t * 4 + j][0], vlo[t * 4 + j][1], vlo[t * 4 + j][2], vlo[t * 4 + j][3], vhi[t * 4 + j][0], vhi[t * 4 + j][1], vhi[t * 4 + j][2], vhi[t * 4 + j][3]};
;                     o[t] = __builtin_amdgcn_mfma_f32_32x32x16_bf16(vf, pw[j], o[t], 0, 0, 0);
;                 }
.Lfx7_pack:
	v_add_f32_e32 v141, v167, v166
	v_cvt_pk_bf16_f32 v66, v106, v107
	v_cvt_pk_bf16_f32 v67, v108, v109
	v_cvt_pk_bf16_f32 v68, v110, v111
	v_cvt_pk_bf16_f32 v69, v112, v113
	v_cvt_pk_bf16_f32 v70, v116, v117
	v_cvt_pk_bf16_f32 v71, v118, v119
	v_cvt_pk_bf16_f32 v72, v120, v121
	v_cvt_pk_bf16_f32 v73, v122, v123
	v_cvt_pk_bf16_f32 v50, v124, v125
	v_cvt_pk_bf16_f32 v51, v126, v127
	v_cvt_pk_bf16_f32 v52, v128, v129
	v_cvt_pk_bf16_f32 v53, v130, v131
	v_cvt_pk_bf16_f32 v54, v132, v133
	v_cvt_pk_bf16_f32 v55, v134, v135
	v_cvt_pk_bf16_f32 v56, v136, v137
	v_cvt_pk_bf16_f32 v57, v138, v139
	v_add_f32_e32 v154, v141, v154
	s_branch .Lfa_end
.Lfa_first:
	v_add_u32_e32 v169, s74, v150
	v_add_u32_e32 v0, s74, v164
	ds_read_b128 v[106:109], v169
	ds_read_b128 v[110:113], v169 offset:4608
	ds_read_b128 v[116:119], v169 offset:32
	ds_read_b128 v[120:123], v169 offset:4640
	ds_read_b128 v[124:127], v169 offset:64
	ds_read_b128 v[128:131], v169 offset:4672
	ds_read_b128 v[132:135], v169 offset:96
	ds_read_b128 v[136:139], v169 offset:4704
	v_mov_b32_e32 v248, s97
	ds_read_b32 v248, v248
	ds_read_b128 v[170:173], v0 offset:128
	ds_read_b128 v[244:247], v0 offset:4736
	s_waitcnt lgkmcnt(10)
	v_mfma_f32_32x32x16_bf16 v[66:81], v[106:109], v[90:93], v[34:49]
	s_waitcnt lgkmcnt(9)
	v_mfma_f32_32x32x16_bf16 v[50:65], v[110:113], v[90:93], v[34:49]
	s_waitcnt lgkmcnt(2)
	v_sub_f32_e32 v249, v160, v248
	v_cvt_pk_bf16_f32 v162, v249, 0
	v_lshlrev_b32_e32 v162, 16, v162
	v_mfma_f32_32x32x16_bf16 v[66:81], v[116:119], v[82:85], v[66:81]
	v_mfma_f32_32x32x16_bf16 v[50:65], v[120:123], v[82:85], v[50:65]
	v_sub_f32_e32 v249, v249, v162
	v_cvt_pk_bf16_f32 v163, v249, 0
	v_and_b32_e32 v157, 0xffff, v163
	v_lshlrev_b32_e32 v163, 16, v163
	v_mfma_f32_32x32x16_bf16 v[66:81], v[124:127], v[86:89], v[66:81]
	v_mfma_f32_32x32x16_bf16 v[50:65], v[128:131], v[86:89], v[50:65]
	v_sub_f32_e32 v249, v249, v163
	v_cvt_pk_bf16_f32 v249, v249, 0
	v_or_b32_e32 v162, 0x3f80, v162
	v_lshl_or_b32 v249, v249, 16, v157
	v_cndmask_b32_e64 v140, 0, v114, s[46:47]
	v_cndmask_b32_e64 v142, 0, v249, s[46:47]
	v_cndmask_b32_e64 v141, 0, v162, s[46:47]
	v_mov_b32_e32 v143, v1
	v_mfma_f32_32x32x16_bf16 v[66:81], v[132:135], v[94:97], v[66:81]
	v_mfma_f32_32x32x16_bf16 v[50:65], v[136:139], v[94:97], v[50:65]
	s_waitcnt lgkmcnt(1)
	v_mfma_f32_32x32x16_bf16 v[66:81], v[170:173], v[140:143], v[66:81]
	s_waitcnt lgkmcnt(0)
	v_mfma_f32_32x32x16_bf16 v[50:65], v[244:247], v[140:143], v[50:65]
	s_branch .Lfa_postqk
.Lfa_last:
	v_add_u32_e32 v168, s75, v161
	ds_read_b64_tr_b16 v[106:107], v168 offset:9216
	ds_read_b64_tr_b16 v[108:109], v168 offset:10752
	ds_read_b64_tr_b16 v[110:111], v168 offset:9280
	ds_read_b64_tr_b16 v[112:113], v168 offset:10816
	ds_read_b64_tr_b16 v[116:117], v168 offset:12288
	ds_read_b64_tr_b16 v[118:119], v168 offset:13824
	ds_read_b64_tr_b16 v[120:121], v168 offset:12352
	ds_read_b64_tr_b16 v[122:123], v168 offset:13888
	ds_read_b64_tr_b16 v[124:125], v168 offset:15360
	ds_read_b64_tr_b16 v[126:127], v168 offset:16896
	ds_read_b64_tr_b16 v[128:129], v168 offset:15424
	ds_read_b64_tr_b16 v[130:131], v168 offset:16960
	ds_read_b64_tr_b16 v[132:133], v168 offset:18432
	ds_read_b64_tr_b16 v[134:135], v168 offset:19968
	ds_read_b64_tr_b16 v[136:137], v168 offset:18496
	ds_read_b64_tr_b16 v[138:139], v168 offset:20032
	s_waitcnt lgkmcnt(14)
	v_mfma_f32_32x32x16_bf16 v[18:33], v[106:109], v[66:69], v[18:33]
	s_waitcnt lgkmcnt(12)
	v_mfma_f32_32x32x16_bf16 v[2:17], v[110:113], v[66:69], v[2:17]
	s_waitcnt lgkmcnt(10)
	v_mfma_f32_32x32x16_bf16 v[18:33], v[116:119], v[70:73], v[18:33]
	s_waitcnt lgkmcnt(8)
	v_mfma_f32_32x32x16_bf16 v[2:17], v[120:123], v[70:73], v[2:17]
	s_waitcnt lgkmcnt(6)
	v_mfma_f32_32x32x16_bf16 v[18:33], v[124:127], v[50:53], v[18:33]
	s_waitcnt lgkmcnt(4)
	v_mfma_f32_32x32x16_bf16 v[2:17], v[128:131], v[50:53], v[2:17]
	s_waitcnt lgkmcnt(2)
	v_mfma_f32_32x32x16_bf16 v[18:33], v[132:135], v[54:57], v[18:33]
	s_waitcnt lgkmcnt(0)
	v_mfma_f32_32x32x16_bf16 v[2:17], v[136:139], v[54:57], v[2:17]

; template <bool DIFF>
; __device__ __forceinline__ void attn_unit(const AttnP& A, int b, int h, int qi, ldsp lds) {
;     ...
;     for (int kt = kt0; kt < nt; ++kt) {
;         if (kt + 1 < nt) LOAD_TILE(kt + 1);
;         if (64 * kt <= qmax_w) {
;             ldsp Kb = lds + (kt & 1) * STAGE; ldsp Vb = Kb + 64 * KP;
;             bf16x8 kf[8]; bf16x8 ka0, ka1, qa; f32x16 s0, s1;
.Lfx10_nold:
.Lfa_end:
	s_waitcnt lgkmcnt(0)
	s_barrier
	s_add_i32 s99, s99, 1
	s_add_i32 s94, s94, 1
	s_add_i32 s97, s97, 4
	s_add_i32 s98, s98, 64
	s_cmp_le_i32 s99, s91
	s_cbranch_scc1 .Lfa_top
	s_add_i32 s0, s91, 1
	s_cmp_eq_u32 s99, s0
	s_cbranch_scc1 .Lfa_top
	s_branch .LBB0_487
.Lfb_top:
	s_bitcmp1_b32 s99, 0
	s_cselect_b32 s74, 0x5500, 0
	s_sub_i32 s75, 0x5500, s74
	s_cmp_eq_u32 s99, s93
	s_cbranch_scc1 .Lfb_first
	s_cmp_gt_i32 s99, s64
	s_cbranch_scc1 .Lfb_stores
	s_add_i32 s1, s98, -64
	s_add_i32 s65, s99, -1
	s_cmp_lg_u32 s65, 0
	s_cselect_b64 s[40:41], -1, 0
	s_cmp_lt_i32 s65, s95
	s_cselect_b64 s[48:49], -1, 0
	s_and_b64 s[50:51], s[40:41], s[48:49]
	s_and_b64 vcc, exec, s[50:51]
	s_cbranch_vccnz .Lfx12_nomask
	v_add_u32_e32 v141, s1, v151
	v_cmp_gt_i32_e32 vcc, 48, v141
	v_cmp_gt_i32_e64 s[48:49], v141, v146
	s_or_b64 vcc, vcc, s[48:49]
	v_add_u32_e32 v142, 32, v141
	v_cndmask_b32_e32 v66, v66, v223, vcc
	v_cmp_gt_i32_e32 vcc, 16, v141
	v_cmp_gt_i32_e64 s[48:49], v142, v146
	s_or_b64 vcc, vcc, s[48:49]
	v_add_u32_e32 v142, 1, v141
	v_cndmask_b32_e32 v50, v50, v223, vcc
	v_cmp_gt_i32_e32 vcc, 48, v142
	v_cmp_ge_i32_e64 s[48:49], v141, v146
	s_or_b64 vcc, s[48:49], vcc
	v_cndmask_b32_e32 v67, v67, v223, vcc
	v_cmp_gt_i32_e32 vcc, 16, v142
	v_add_u32_e32 v142, 33, v141
	v_cmp_gt_i32_e64 s[48:49], v142, v146
	s_or_b64 vcc, vcc, s[48:49]
	v_add_u32_e32 v142, 2, v141
	v_cndmask_b32_e32 v51, v51, v223, vcc
	v_cmp_gt_i32_e32 vcc, 48, v142
	v_cmp_gt_i32_e64 s[48:49], v142, v146
	s_or_b64 vcc, vcc, s[48:49]
	v_cndmask_b32_e32 v68, v68, v223, vcc
	v_cmp_gt_i32_e32 vcc, 16, v142
	v_add_u32_e32 v142, 34, v141
	v_cmp_gt_i32_e64 s[48:49], v142, v146
	s_or_b64 vcc, vcc, s[48:49]
	v_add_u32_e32 v142, 3, v141
	v_cndmask_b32_e32 v52, v52, v223, vcc
	v_cmp_gt_i32_e32 vcc, 48, v142
	v_cmp_gt_i32_e64 s[48:49], v142, v146
	s_or_b64 vcc, vcc, s[48:49]
	v_cndmask_b32_e32 v69, v69, v223, vcc
	v_cmp_gt_i32_e32 vcc, 16, v142
	v_add_u32_e32 v142, 35, v141
	v_cmp_gt_i32_e64 s[48:49], v142, v146
	s_or_b64 vcc, vcc, s[48:49]
	v_add_u32_e32 v142, 8, v141
	v_cndmask_b32_e32 v53, v53, v223, vcc
	v_cmp_gt_i32_e32 vcc, 48, v142
	v_cmp_gt_i32_e64 s[48:49], v142, v146
	s_or_b64 vcc, vcc, s[48:49]
	v_cndmask_b32_e32 v70, v70, v223, vcc
	v_cmp_gt_i32_e32 vcc, 16, v142
	v_add_u32_e32 v142, 40, v141
	v_cmp_gt_i32_e64 s[48:49], v142, v146
	s_or_b64 vcc, vcc, s[48:49]
	v_add_u32_e32 v142, 9, v141
	v_cndmask_b32_e32 v54, v54, v223, vcc
	v_cmp_gt_i32_e32 vcc, 48, v142
	v_cmp_gt_i32_e64 s[48:49], v142, v146
	s_or_b64 vcc, vcc, s[48:49]
	v_cndmask_b32_e32 v71, v71, v223, vcc
	v_cmp_gt_i32_e32 vcc, 16, v142
	v_add_u32_e32 v142, 41, v141
	v_cmp_gt_i32_e64 s[48:49], v142, v146
	s_or_b64 vcc, vcc, s[48:49]
	v_add_u32_e32 v142, 10, v141
	v_cndmask_b32_e32 v55, v55, v223, vcc
	v_cmp_gt_i32_e32 vcc, 48, v142
	v_cmp_gt_i32_e64 s[48:49], v142, v146
	s_or_b64 vcc, vcc, s[48:49]
	v_cndmask_b32_e32 v72, v72, v223, vcc
	v_cmp_gt_i32_e32 vcc, 16, v142
	v_add_u32_e32 v142, 42, v141
	v_cmp_gt_i32_e64 s[48:49], v142, v146
	s_or_b64 vcc, vcc, s[48:49]
	v_add_u32_e32 v142, 11, v141
	v_cndmask_b32_e32 v56, v56, v223, vcc
	v_cmp_gt_i32_e32 vcc, 48, v142
	v_cmp_gt_i32_e64 s[48:49], v142, v146
	s_or_b64 vcc, vcc, s[48:49]
	v_cndmask_b32_e32 v73, v73, v223, vcc
	v_cmp_gt_i32_e32 vcc, 16, v142
	v_add_u32_e32 v142, 43, v141
	v_cmp_gt_i32_e64 s[48:49], v142, v146
	s_or_b64 vcc, vcc, s[48:49]
	v_add_u32_e32 v142, 16, v141
	v_cndmask_b32_e32 v57, v57, v223, vcc
	v_cmp_gt_i32_e32 vcc, 48, v142
	v_cmp_gt_i32_e64 s[48:49], v142, v146
	s_or_b64 vcc, vcc, s[48:49]
	s_cmp_lt_i32 s65, 0
	v_add_u32_e32 v142, 48, v141
	v_cndmask_b32_e32 v74, v74, v223, vcc
	s_cselect_b64 s[40:41], -1, 0
	v_cmp_gt_i32_e32 vcc, v142, v146
	s_or_b64 vcc, s[40:41], vcc
	v_add_u32_e32 v142, 17, v141
	v_cndmask_b32_e32 v58, v58, v223, vcc
	v_cmp_gt_i32_e32 vcc, 48, v142
	v_cmp_gt_i32_e64 s[48:49], v142, v146
	s_or_b64 vcc, vcc, s[48:49]
	v_add_u32_e32 v142, 49, v141
	v_cndmask_b32_e32 v75, v75, v223, vcc
	v_cmp_gt_i32_e32 vcc, v142, v146
	s_or_b64 vcc, s[40:41], vcc
	v_add_u32_e32 v142, 18, v141
	v_cndmask_b32_e32 v59, v59, v223, vcc
	v_cmp_gt_i32_e32 vcc, 48, v142
	v_cmp_gt_i32_e64 s[48:49], v142, v146
	s_or_b64 vcc, vcc, s[48:49]
	v_add_u32_e32 v142, 50, v141
	v_cndmask_b32_e32 v76, v76, v223, vcc
	v_cmp_gt_i32_e32 vcc, v142, v146
	s_or_b64 vcc, s[40:41], vcc
	v_add_u32_e32 v142, 19, v141
	v_cndmask_b32_e32 v60, v60, v223, vcc
	v_cmp_gt_i32_e32 vcc, 48, v142
	v_cmp_gt_i32_e64 s[48:49], v142, v146
	s_or_b64 vcc, vcc, s[48:49]
	v_add_u32_e32 v142, 51, v141
	v_cndmask_b32_e32 v77, v77, v223, vcc
	v_cmp_gt_i32_e32 vcc, v142, v146
	s_or_b64 vcc, s[40:41], vcc
	v_add_u32_e32 v142, 24, v141
	v_cndmask_b32_e32 v61, v61, v223, vcc
	v_cmp_gt_i32_e32 vcc, 48, v142
	v_cmp_gt_i32_e64 s[48:49], v142, v146
	s_or_b64 vcc, vcc, s[48:49]
	v_add_u32_e32 v142, 56, v141
	v_cndmask_b32_e32 v78, v78, v223, vcc
	v_cmp_gt_i32_e32 vcc, v142, v146
	s_or_b64 vcc, s[40:41], vcc
	v_add_u32_e32 v142, 25, v141
	v_cndmask_b32_e32 v62, v62, v223, vcc
	v_cmp_gt_i32_e32 vcc, 48, v142
	v_cmp_gt_i32_e64 s[48:49], v142, v146
	s_or_b64 vcc, vcc, s[48:49]
	v_add_u32_e32 v142, 57, v141
	v_cndmask_b32_e32 v79, v79, v223, vcc
	v_cmp_gt_i32_e32 vcc, v142, v146
	s_or_b64 vcc, s[40:41], vcc
	v_add_u32_e32 v142, 26, v141
	v_cndmask_b32_e32 v63, v63, v223, vcc
	v_cmp_gt_i32_e32 vcc, 48, v142
	v_cmp_gt_i32_e64 s[48:49], v142, v146
	s_or_b64 vcc, vcc, s[48:49]
	v_add_u32_e32 v142, 58, v141
	v_cndmask_b32_e32 v80, v80, v223, vcc
	v_cmp_gt_i32_e32 vcc, v142, v146
	s_or_b64 vcc, s[40:41], vcc
	v_add_u32_e32 v142, 27, v141
	v_cndmask_b32_e32 v64, v64, v223, vcc
	v_cmp_gt_i32_e32 vcc, 48, v142
	v_cmp_gt_i32_e64 s[48:49], v142, v146
	s_or_b64 vcc, vcc, s[48:49]
	v_add_u32_e32 v141, 59, v141
	v_cndmask_b32_e32 v81, v81, v223, vcc
	v_cmp_gt_i32_e32 vcc, v141, v146
	s_or_b64 vcc, s[40:41], vcc
	s_nop 0
	v_cndmask_b32_e32 v65, v65, v223, vcc
; #define EXPSUM_BLOCK() do { psa = 0.f; psb = 0.f; \
;             _Pragma("unroll") for (int r = 0; r < 16; ++r) { s0[r] = __builtin_amdgcn_exp2f(s0[r]); s1[r] = __builtin_amdgcn_exp2f(s1[r]); psa += s0[r]; asm("" : "+v"(psa)); psb += s1[r]; asm("" : "+v"(psb)); } } while (0)
; template <bool DIFF>
; __device__ __forceinline__ void attn_unit(const AttnP& A, int b, int h, int qi, ldsp lds) {
;     ...
;             bool full = (kt == kt0);
;             float psa, psb;
;             if (!full) {
;                 EXPSUM_BLOCK();
;                 if (__any(psa + psb > 1.0e18f)) { full = true; QK_BLOCK();
.Lfx12_nomask:
	s_cmp_eq_u32 s65, s93
	s_cselect_b64 s[48:49], -1, 0
	s_and_b64 vcc, exec, s[48:49]
	s_cbranch_vccnz .Lfx13_full
	v_exp_f32_e32 v106, v66
	v_exp_f32_e32 v124, v50
	v_exp_f32_e32 v107, v67
	v_exp_f32_e32 v125, v51
	v_add_f32_e32 v166, 0, v106
	v_add_f32_e32 v167, 0, v124
	v_exp_f32_e32 v108, v68
	v_exp_f32_e32 v126, v52
	v_add_f32_e32 v166, v107, v166
	v_add_f32_e32 v167, v125, v167
	v_exp_f32_e32 v109, v69
	v_exp_f32_e32 v127, v53
	v_add_f32_e32 v166, v108, v166
	v_add_f32_e32 v167, v126, v167
	v_exp_f32_e32 v110, v70
	v_exp_f32_e32 v128, v54
	v_add_f32_e32 v166, v109, v166
	v_add_f32_e32 v167, v127, v167
	v_exp_f32_e32 v111, v71
	v_exp_f32_e32 v129, v55
	v_add_f32_e32 v166, v110, v166
	v_add_f32_e32 v167, v128, v167
	v_exp_f32_e32 v112, v72
	v_exp_f32_e32 v130, v56
	v_add_f32_e32 v166, v111, v166
	v_add_f32_e32 v167, v129, v167
	v_exp_f32_e32 v113, v73
	v_exp_f32_e32 v131, v57
	v_add_f32_e32 v166, v112, v166
	v_add_f32_e32 v167, v130, v167
	v_exp_f32_e32 v116, v74
	v_exp_f32_e32 v132, v58
	v_add_f32_e32 v166, v113, v166
	v_add_f32_e32 v167, v131, v167
	v_exp_f32_e32 v117, v75
	v_exp_f32_e32 v133, v59
	v_add_f32_e32 v166, v116, v166
	v_add_f32_e32 v167, v132, v167
	v_exp_f32_e32 v118, v76
	v_exp_f32_e32 v134, v60
	v_add_f32_e32 v166, v117, v166
	v_add_f32_e32 v167, v133, v167
	v_exp_f32_e32 v119, v77
	v_exp_f32_e32 v135, v61
	v_add_f32_e32 v166, v118, v166
	v_add_f32_e32 v167, v134, v167
	v_exp_f32_e32 v120, v78
	v_exp_f32_e32 v136, v62
	v_add_f32_e32 v166, v119, v166
	v_add_f32_e32 v167, v135, v167
	v_exp_f32_e32 v121, v79
	v_exp_f32_e32 v137, v63
	v_add_f32_e32 v166, v120, v166
	v_add_f32_e32 v167, v136, v167
	v_exp_f32_e32 v122, v80
	v_exp_f32_e32 v138, v64
	v_add_f32_e32 v166, v121, v166
	v_add_f32_e32 v167, v137, v167
	v_exp_f32_e32 v123, v81
	v_exp_f32_e32 v139, v65
	v_add_f32_e32 v166, v122, v166
	v_add_f32_e32 v167, v138, v167
	s_nop 0
	v_add_f32_e32 v166, v123, v166
	v_add_f32_e32 v167, v139, v167
	v_add_f32_e32 v141, v166, v167
	v_cmp_lt_f32_e32 vcc, s85, v141
	s_cbranch_vccz .Lfx14_pack

; __device__ __forceinline__ unsigned cvtpk(float lo, float hi) { f32x2 v = {lo, hi}; bf16x2_t b = __builtin_convertvector(v, bf16x2_t); return __builtin_bit_cast(unsigned, b); }
; template <bool DIFF>
; __device__ __forceinline__ void attn_unit(const AttnP& A, int b, int h, int qi, ldsp lds) {
;     ...
;             bf16x8 pw[4];
; #pragma unroll
;             for (int j = 0; j < 4; ++j) {
;                 u32x4 pk;
;                 if (j < 2) { const int rb = 8 * (j & 1); pk.x = cvtpk(s0[rb], s0[rb + 1]); pk.y = cvtpk(s0[rb + 2], s0[rb + 3]); pk.z = cvtpk(s0[rb + 4], s0[rb + 5]); pk.w = cvtpk(s0[rb + 6], s0[rb + 7]); }
;                 else { const int rb = 8 * (j & 1); pk.x = cvtpk(s1[rb], s1[rb + 1]); pk.y = cvtpk(s1[rb + 2], s1[rb + 3]); pk.z = cvtpk(s1[rb + 4], s1[rb + 5]); pk.w = cvtpk(s1[rb + 6], s1[rb + 7]); }
;                 pw[j] = __builtin_bit_cast(bf16x8, pk);
;             }
;             __builtin_amdgcn_sched_barrier(0);
;             __builtin_amdgcn_s_setprio(1);
; #pragma unroll
;             for (int t = 0; t < 2; ++t)
; #pragma unroll
;                 for (int j = 0; j < 4; ++j) {
;                     const bf16x8 vf = (bf16x8){vlo[t * 4 + j][0], vlo[t * 4 + j][1], vlo[t * 4 + j][2], vlo[t * 4 + j][3], vhi[t * 4 + j][0], vhi[t * 4 + j][1], vhi[t * 4 + j][2], vhi[t * 4 + j][3]};
;                     o[t] = __builtin_amdgcn_mfma_f32_32x32x16_bf16(vf, pw[j], o[t], 0, 0, 0);
;                 }
.Lfx14_pack:
	v_add_u32_e32 v169, s74, v150
	v_add_u32_e32 v0, s74, v164
	v_add_u32_e32 v168, s75, v161
	ds_read_b64_tr_b16 v[58:59], v168 offset:9216
	ds_read_b64_tr_b16 v[60:61], v168 offset:10752
	ds_read_b64_tr_b16 v[62:63], v168 offset:9280
	ds_read_b64_tr_b16 v[64:65], v168 offset:10816
	ds_read_b64_tr_b16 v[74:75], v168 offset:12288
	ds_read_b64_tr_b16 v[76:77], v168 offset:13824
	ds_read_b64_tr_b16 v[78:79], v168 offset:12352
	ds_read_b64_tr_b16 v[80:81], v168 offset:13888
	ds_read_b64_tr_b16 v[244:245], v168 offset:15360
	ds_read_b64_tr_b16 v[246:247], v168 offset:16896
	v_add_f32_e32 v141, v167, v166
	v_cvt_pk_bf16_f32 v66, v106, v107
	v_cvt_pk_bf16_f32 v67, v108, v109
	v_cvt_pk_bf16_f32 v68, v110, v111
	v_cvt_pk_bf16_f32 v69, v112, v113
	v_cvt_pk_bf16_f32 v70, v116, v117
	v_cvt_pk_bf16_f32 v71, v118, v119
	v_cvt_pk_bf16_f32 v72, v120, v121
	v_cvt_pk_bf16_f32 v73, v122, v123
	v_cvt_pk_bf16_f32 v50, v124, v125
	v_cvt_pk_bf16_f32 v51, v126, v127
	v_cvt_pk_bf16_f32 v52, v128, v129
	v_cvt_pk_bf16_f32 v53, v130, v131
	v_cvt_pk_bf16_f32 v54, v132, v133
	v_cvt_pk_bf16_f32 v55, v134, v135
	v_cvt_pk_bf16_f32 v56, v136, v137
	v_cvt_pk_bf16_f32 v57, v138, v139
	v_add_f32_e32 v154, v141, v154
	ds_read_b64_tr_b16 v[106:107], v168 offset:15424
	ds_read_b64_tr_b16 v[108:109], v168 offset:16960
	ds_read_b64_tr_b16 v[110:111], v168 offset:18432
	ds_read_b64_tr_b16 v[112:113], v168 offset:19968
	ds_read_b64_tr_b16 v[116:117], v168 offset:18496
	ds_read_b64_tr_b16 v[118:119], v168 offset:20032
	s_cmp_eq_u32 s99, s64
	s_cbranch_scc1 .Lfb_last
	v_mov_b32_e32 v248, s97
	ds_read_b32 v248, v248
	ds_read_b128 v[120:123], v169
	ds_read_b128 v[124:127], v169 offset:4608
	ds_read_b128 v[128:131], v169 offset:32
	ds_read_b128 v[132:135], v169 offset:4640
	ds_read_b128 v[136:139], v169 offset:64
	ds_read_b128 v[170:173], v169 offset:4672
	s_waitcnt lgkmcnt(15)
	v_mfma_f32_32x32x16_bf16 v[18:33], v[58:61], v[66:69], v[18:33]
	v_mfma_f32_32x32x16_bf16 v[2:17], v[62:65], v[66:69], v[2:17]
	v_mfma_f32_32x32x16_bf16 v[18:33], v[74:77], v[70:73], v[18:33]
	v_mfma_f32_32x32x16_bf16 v[2:17], v[78:81], v[70:73], v[2:17]
	s_waitcnt lgkmcnt(13)
	v_mfma_f32_32x32x16_bf16 v[18:33], v[244:247], v[50:53], v[18:33]
	ds_read_b128 v[244:247], v169 offset:96
	s_waitcnt lgkmcnt(12)
	v_mfma_f32_32x32x16_bf16 v[2:17], v[106:109], v[50:53], v[2:17]
	ds_read_b128 v[106:109], v169 offset:4704
	s_waitcnt lgkmcnt(11)
	v_mfma_f32_32x32x16_bf16 v[18:33], v[110:113], v[54:57], v[18:33]
	ds_read_b128 v[110:113], v0 offset:128
	s_waitcnt lgkmcnt(10)
	v_mfma_f32_32x32x16_bf16 v[2:17], v[116:119], v[54:57], v[2:17]
	ds_read_b128 v[116:119], v0 offset:4736
	s_waitcnt lgkmcnt(9)
	v_mfma_f32_32x32x16_bf16 v[66:81], v[120:123], v[90:93], v[34:49]
	s_waitcnt lgkmcnt(8)
	v_mfma_f32_32x32x16_bf16 v[50:65], v[124:127], v[90:93], v[34:49]
	v_sub_f32_e32 v249, v160, v248
	v_cvt_pk_bf16_f32 v162, v249, 0
	v_lshlrev_b32_e32 v162, 16, v162
	s_waitcnt lgkmcnt(7)
	v_mfma_f32_32x32x16_bf16 v[66:81], v[128:131], v[82:85], v[66:81]
	s_waitcnt lgkmcnt(6)
	v_mfma_f32_32x32x16_bf16 v[50:65], v[132:135], v[82:85], v[50:65]
	v_sub_f32_e32 v249, v249, v162
	v_cvt_pk_bf16_f32 v163, v249, 0
	v_and_b32_e32 v157, 0xffff, v163
	v_lshlrev_b32_e32 v163, 16, v163
	s_waitcnt lgkmcnt(5)
	v_mfma_f32_32x32x16_bf16 v[66:81], v[136:139], v[86:89], v[66:81]
	s_waitcnt lgkmcnt(4)
	v_mfma_f32_32x32x16_bf16 v[50:65], v[170:173], v[86:89], v[50:65]
	v_sub_f32_e32 v249, v249, v163
	v_cvt_pk_bf16_f32 v249, v249, 0
	v_or_b32_e32 v162, 0x3f80, v162
	v_lshl_or_b32 v249, v249, 16, v157
	v_cndmask_b32_e64 v140, 0, v114, s[46:47]
	v_cndmask_b32_e64 v142, 0, v249, s[46:47]
	v_cndmask_b32_e64 v141, 0, v162, s[46:47]
	v_mov_b32_e32 v143, v1
	s_waitcnt lgkmcnt(3)
	v_mfma_f32_32x32x16_bf16 v[66:81], v[244:247], v[94:97], v[66:81]
	s_waitcnt lgkmcnt(2)
	v_mfma_f32_32x32x16_bf16 v[50:65], v[106:109], v[94:97], v[50:65]
	s_waitcnt lgkmcnt(1)
	v_mfma_f32_32x32x16_bf16 v[66:81], v[110:113], v[140:143], v[66:81]
	s_waitcnt lgkmcnt(0)
	v_mfma_f32_32x32x16_bf16 v[50:65], v[116:119], v[140:143], v[50:65]
	s_branch .Lfb_stores
.Lfb_last:
	s_waitcnt lgkmcnt(14)
	v_mfma_f32_32x32x16_bf16 v[18:33], v[58:61], v[66:69], v[18:33]
	s_waitcnt lgkmcnt(12)
	v_mfma_f32_32x32x16_bf16 v[2:17], v[62:65], v[66:69], v[2:17]
	s_waitcnt lgkmcnt(10)
	v_mfma_f32_32x32x16_bf16 v[18:33], v[74:77], v[70:73], v[18:33]
	s_waitcnt lgkmcnt(8)
	v_mfma_f32_32x32x16_bf16 v[2:17], v[78:81], v[70:73], v[2:17]
	s_waitcnt lgkmcnt(6)
	v_mfma_f32_32x32x16_bf16 v[18:33], v[244:247], v[50:53], v[18:33]
	s_waitcnt lgkmcnt(4)
	v_mfma_f32_32x32x16_bf16 v[2:17], v[106:109], v[50:53], v[2:17]
	s_waitcnt lgkmcnt(2)
	v_mfma_f32_32x32x16_bf16 v[18:33], v[110:113], v[54:57], v[18:33]
	s_waitcnt lgkmcnt(0)
	v_mfma_f32_32x32x16_bf16 v[2:17], v[116:119], v[54:57], v[2:17]
	s_branch .Lfb_stores
.Lfb_first:
	v_add_u32_e32 v169, s74, v150
	v_add_u32_e32 v0, s74, v164
	ds_read_b128 v[106:109], v169
	ds_read_b128 v[110:113], v169 offset:4608
	ds_read_b128 v[116:119], v169 offset:32
	ds_read_b128 v[120:123], v169 offset:4640
	ds_read_b128 v[124:127], v169 offset:64
	ds_read_b128 v[128:131], v169 offset:4672
	ds_read_b128 v[132:135], v169 offset:96
	ds_read_b128 v[136:139], v169 offset:4704
	v_mov_b32_e32 v248, s97
	ds_read_b32 v248, v248
	ds_read_b128 v[170:173], v0 offset:128
	ds_read_b128 v[244:247], v0 offset:4736
	s_waitcnt lgkmcnt(10)
	v_mfma_f32_32x32x16_bf16 v[66:81], v[106:109], v[90:93], v[34:49]
	s_waitcnt lgkmcnt(9)
	v_mfma_f32_32x32x16_bf16 v[50:65], v[110:113], v[90:93], v[34:49]
	s_waitcnt lgkmcnt(2)
	v_sub_f32_e32 v249, v160, v248
	v_cvt_pk_bf16_f32 v162, v249, 0
	v_lshlrev_b32_e32 v162, 16, v162
	v_mfma_f32_32x32x16_bf16 v[66:81], v[116:119], v[82:85], v[66:81]
	v_mfma_f32_32x32x16_bf16 v[50:65], v[120:123], v[82:85], v[50:65]
	v_sub_f32_e32 v249, v249, v162
	v_cvt_pk_bf16_f32 v163, v249, 0
	v_and_b32_e32 v157, 0xffff, v163
	v_lshlrev_b32_e32 v163, 16, v163
	v_mfma_f32_32x32x16_bf16 v[66:81], v[124:127], v[86:89], v[66:81]
	v_mfma_f32_32x32x16_bf16 v[50:65], v[128:131], v[86:89], v[50:65]
	v_sub_f32_e32 v249, v249, v163
	v_cvt_pk_bf16_f32 v249, v249, 0
	v_or_b32_e32 v162, 0x3f80, v162
	v_lshl_or_b32 v249, v249, 16, v157
	v_cndmask_b32_e64 v140, 0, v114, s[46:47]
	v_cndmask_b32_e64 v142, 0, v249, s[46:47]
	v_cndmask_b32_e64 v141, 0, v162, s[46:47]
	v_mov_b32_e32 v143, v1
	v_mfma_f32_32x32x16_bf16 v[66:81], v[132:135], v[94:97], v[66:81]
	v_mfma_f32_32x32x16_bf16 v[50:65], v[136:139], v[94:97], v[50:65]
	s_waitcnt lgkmcnt(1)
	v_mfma_f32_32x32x16_bf16 v[66:81], v[170:173], v[140:143], v[66:81]
	s_waitcnt lgkmcnt(0)
	v_mfma_f32_32x32x16_bf16 v[50:65], v[244:247], v[140:143], v[50:65]

; template <bool DIFF>
; __device__ __forceinline__ void attn_unit(const AttnP& A, int b, int h, int qi, ldsp lds) {
;     ...
;     for (int kt = kt0; kt < nt; ++kt) {
;         if (kt + 1 < nt) LOAD_TILE(kt + 1);
;         if (64 * kt <= qmax_w) {
;             ldsp Kb = lds + (kt & 1) * STAGE; ldsp Vb = Kb + 64 * KP;
;             bf16x8 kf[8]; bf16x8 ka0, ka1, qa; f32x16 s0, s1;
;     ...
;         if (kt + 1 < nt) STORE_TILE((kt + 1) & 1);
;         __syncthreads();
.Lfx17_nold:
	s_waitcnt lgkmcnt(0)
	s_barrier
	s_add_i32 s99, s99, 1
	s_add_i32 s94, s94, 1
	s_add_i32 s97, s97, 4
	s_add_i32 s98, s98, 64
	s_cmp_le_i32 s99, s91
	s_cbranch_scc1 .Lfb_top
	s_add_i32 s0, s91, 1
	s_cmp_eq_u32 s99, s0
	s_cbranch_scc1 .Lfb_top
	s_branch .LBB0_487
